# ATT2F loop back-edge rotation: loop control, next tile's bias init and K-read addresses computed before the end-of-tile barrier
# speedup vs baseline: 1.0112x; 1.0013x over previous
; template <bool DIFF, bool FIXED, bool F32SRC> ...
;     ...
;         const int b2 = (buf >= 1) ? buf - 1 : 2;
;         if (j - 2 >= u.jlo) ATT_DMA(j - 2, b2);
.Lbb415:
	s_andn2_b64 vcc, exec, s[16:17]
	s_cbranch_vccnz .Lnc_nodma
	s_ashr_i32 s13, s12, 31
	s_lshl_b64 s[18:19], s[12:13], 11
	s_add_u32 s66, s50, s18
	s_addc_u32 s67, s60, s19
	s_add_u32 s18, s63, s18
	s_addc_u32 s19, s64, s19
	s_lshl_b32 s13, s28, 15
	s_addk_i32 s13, 0x8000
	s_cmp_gt_i32 s28, 0
	s_cselect_b32 s13, s13, 0x10000
	s_add_i32 s13, s51, s13
	v_lshl_add_u64 v[66:67], v[136:137], 1, s[66:67]
	s_mov_b32 m0, s13
	s_nop 0
	global_load_lds_dwordx4 v[66:67], off
	v_lshl_add_u64 v[66:67], v[138:139], 1, s[18:19]
	s_add_i32 m0, s13, 0x4000
	s_nop 0
	global_load_lds_dwordx4 v[66:67], off
	v_lshl_add_u64 v[66:67], v[140:141], 1, s[66:67]
	s_add_i32 m0, s13, 0x400
	s_nop 0
	global_load_lds_dwordx4 v[66:67], off
	v_lshl_add_u64 v[66:67], v[142:143], 1, s[18:19]
	s_add_i32 m0, s13, 0x4400
	s_nop 0
	global_load_lds_dwordx4 v[66:67], off
	s_add_i32 s13, s25, 2

; #define LAS __attribute__((address_space(3)))
; #define MFMA32(a, b, c) __builtin_amdgcn_mfma_f32_32x32x16_bf16((a), (b), (c), 0, 0, 0)
; template <bool DIFF, bool FIXED, bool F32SRC> ...
;     ...
;                 if (j < cq) {
;                     const float base = -slopeL2 * dq - mrun;
; #pragma unroll
;                     for (int r = 0; r < 16; ++r) { const float c = (float)((r & 3) + 8 * (r >> 2)); a0[r] = slopeL2 * c + base; a1[r] = slopeL2 * (c + 32.f) + base; }
;     ...
;             for (int ks = 0; ks < 2; ++ks) { a0 = MFMA32(kf0[ks], qf[ks], a0); a1 = MFMA32(kf1[ks], qf[ks], a1); }
;             __builtin_amdgcn_sched_barrier(0);
; #pragma unroll
;             for (int ks = 0; ks < 2; ++ks) { kf0[ks] = *(const LAS bf16x8*)(kb + koff[ks + 2]); kf1[ks] = *(const LAS bf16x8*)(kb + koff[ks + 2] + 32 * RB); }
;             __builtin_amdgcn_sched_barrier(0);
; #pragma unroll
;             for (int ks = 0; ks < 2; ++ks) { a0 = MFMA32(kf0[ks], qf[ks + 2], a0); a1 = MFMA32(kf1[ks], qf[ks + 2], a1); }
.LBB0_419:
	s_andn2_b64 vcc, exec, s[18:19]
	s_cbranch_vccnz .LBB0_421
	v_fma_f32 v235, -v135, v0, -v132
	v_add_f32_e32 v80, v174, v235
	v_add_f32_e32 v81, v175, v235
	v_add_f32_e32 v78, v172, v235
	v_add_f32_e32 v79, v173, v235
	v_add_f32_e32 v76, v170, v235
	v_add_f32_e32 v77, v171, v235
	v_add_f32_e32 v74, v168, v235
	v_add_f32_e32 v75, v169, v235
	v_add_f32_e32 v72, v166, v235
	v_add_f32_e32 v73, v167, v235
	v_add_f32_e32 v70, v164, v235
	v_add_f32_e32 v71, v165, v235
	v_add_f32_e32 v68, v162, v235
	v_add_f32_e32 v69, v163, v235
	v_add_f32_e32 v66, v134, v235
	v_add_f32_e32 v67, v135, v235
.Lqk_pre:
	s_waitcnt lgkmcnt(4)
	v_add_f32_e32 v96, v178, v235
	v_mfma_f32_32x32x16_bf16 v[66:81], v[114:117], v[98:101], v[66:81]
	v_add_f32_e32 v97, v179, v235
	v_add_f32_e32 v94, v180, v235
	v_add_f32_e32 v95, v181, v235
	v_add_f32_e32 v92, v182, v235
	v_add_f32_e32 v93, v183, v235
	v_mfma_f32_32x32x16_bf16 v[66:81], v[118:121], v[102:105], v[66:81]
	v_add_f32_e32 v90, v184, v235
	v_add_f32_e32 v91, v185, v235
	v_add_f32_e32 v88, v186, v235
	v_add_f32_e32 v89, v187, v235
	v_add_f32_e32 v86, v188, v235
	v_mfma_f32_32x32x16_bf16 v[66:81], v[122:125], v[106:109], v[66:81]
	v_add_f32_e32 v87, v189, v235
	v_add_f32_e32 v84, v190, v235
	v_add_f32_e32 v85, v191, v235
	v_add_f32_e32 v82, v192, v235
	v_add_f32_e32 v83, v193, v235
	v_mfma_f32_32x32x16_bf16 v[66:81], v[126:129], v[110:113], v[66:81]
	s_branch .Lqk4_done

; __device__ __forceinline__ unsigned cvt_pk_bf16(float lo, float hi) { unsigned r; asm volatile("v_cvt_pk_bf16_f32 %0, %1, %2" : "=v"(r) : "v"(lo), "v"(hi)); return r; }
; #define MFMA32(a, b, c) __builtin_amdgcn_mfma_f32_32x32x16_bf16((a), (b), (c), 0, 0, 0)
; #define ATT_VLOAD(dst, db) do { _Pragma("unroll") for (int ks = 0; ks < 4; ++ks) { \
;                 const s16x4 lo_ = vtr(vb + (2 * ks) * (NDB * 512) + (db) * 512 + vlane), h4_ = vtr(vb + (2 * ks + 1) * (NDB * 512) + (db) * 512 + vlane); \
;                 dst[ks] = (bf16x8){lo_[0], lo_[1], lo_[2], lo_[3], h4_[0], h4_[1], h4_[2], h4_[3]}; } } while (0)
; template <bool DIFF, bool FIXED, bool F32SRC> ...
;     ...
;             float ls = 0.f;
; #pragma unroll
;             for (int r = 0; r < 16; ++r) { a0[r] = __builtin_amdgcn_exp2f(a0[r]); a1[r] = __builtin_amdgcn_exp2f(a1[r]); ls += a0[r] + a1[r]; }
;             lrun += ls;
;             bf16x8 pf[4];
; #pragma unroll
;             for (int ks = 0; ks < 4; ++ks) { u32x4 p;
; #pragma unroll
;                 for (int e = 0; e < 4; ++e) p[e] = (ks < 2) ? cvt_pk_bf16(a0[8 * ks + 2 * e], a0[8 * ks + 2 * e + 1]) : cvt_pk_bf16(a1[8 * (ks - 2) + 2 * e], a1[8 * (ks - 2) + 2 * e + 1]);
;                 pf[ks] = __builtin_bit_cast(bf16x8, p); }
; #pragma unroll
;             for (int db = 0; db < NDB; ++db) {
;                 ATT_VLOAD(vf, db);
;                 __builtin_amdgcn_sched_barrier(0);
; #pragma unroll
;                 for (int ks = 0; ks < 4; ++ks) o[db] = MFMA32(vf[ks], pf[ks], o[db]);
;                 __builtin_amdgcn_sched_barrier(0);
;             }
.Lqk4_done:
	v_add_u32_e32 v0, s66, v225
	ds_read_b64_tr_b16 v[114:115], v0 offset:16384
	ds_read_b64_tr_b16 v[116:117], v0 offset:18432
	ds_read_b64_tr_b16 v[118:119], v0 offset:16896
	ds_read_b64_tr_b16 v[120:121], v0 offset:18944
	ds_read_b64_tr_b16 v[122:123], v0 offset:17408
	ds_read_b64_tr_b16 v[124:125], v0 offset:19456
	ds_read_b64_tr_b16 v[126:127], v0 offset:17920
	ds_read_b64_tr_b16 v[128:129], v0 offset:19968
	s_waitcnt lgkmcnt(8)
	v_mfma_f32_32x32x16_bf16 v[82:97], v[146:149], v[98:101], v[82:97]
	s_nop 1
	v_exp_f32_e32 v66, v66
	v_exp_f32_e32 v67, v67
	v_exp_f32_e32 v68, v68
	v_mfma_f32_32x32x16_bf16 v[82:97], v[150:153], v[102:105], v[82:97]
	v_exp_f32_e32 v69, v69
	v_exp_f32_e32 v70, v70
	v_exp_f32_e32 v71, v71
	v_mfma_f32_32x32x16_bf16 v[82:97], v[154:157], v[106:109], v[82:97]
	v_exp_f32_e32 v72, v72
	v_exp_f32_e32 v73, v73
	v_add_f32_e32 v228, v66, v67
	v_add_f32_e32 v229, v68, v69
	v_cvt_pk_bf16_f32 v66, v66, v67
	v_mfma_f32_32x32x16_bf16 v[82:97], v[158:161], v[110:113], v[82:97]
	v_add_f32_e32 v228, v228, v70
	v_add_f32_e32 v229, v229, v71
	v_cvt_pk_bf16_f32 v67, v68, v69
	v_add_f32_e32 v228, v228, v72
	v_add_f32_e32 v229, v229, v73
	v_cvt_pk_bf16_f32 v68, v70, v71
	v_cvt_pk_bf16_f32 v69, v72, v73
	s_waitcnt lgkmcnt(7)
	ds_read_b64_tr_b16 v[146:147], v0 offset:20480
	ds_read_b64_tr_b16 v[148:149], v0 offset:22528
	ds_read_b64_tr_b16 v[150:151], v0 offset:20992
	ds_read_b64_tr_b16 v[152:153], v0 offset:23040
	ds_read_b64_tr_b16 v[154:155], v0 offset:21504
	ds_read_b64_tr_b16 v[156:157], v0 offset:23552
	ds_read_b64_tr_b16 v[158:159], v0 offset:22016
	ds_read_b64_tr_b16 v[160:161], v0 offset:24064
	s_waitcnt lgkmcnt(8)
	v_mfma_f32_32x32x16_bf16 v[50:65], v[114:117], v[66:69], v[50:65]
	v_exp_f32_e32 v74, v74
	v_exp_f32_e32 v75, v75
	v_exp_f32_e32 v76, v76
	v_mfma_f32_32x32x16_bf16 v[34:49], v[118:121], v[66:69], v[34:49]
	v_exp_f32_e32 v77, v77
	v_exp_f32_e32 v78, v78
	v_add_f32_e32 v228, v228, v74
	v_add_f32_e32 v229, v229, v75
	v_cvt_pk_bf16_f32 v70, v74, v75
	v_mfma_f32_32x32x16_bf16 v[18:33], v[122:125], v[66:69], v[18:33]
	v_exp_f32_e32 v79, v79
	v_exp_f32_e32 v80, v80
	v_add_f32_e32 v228, v228, v76
	v_add_f32_e32 v229, v229, v77
	v_cvt_pk_bf16_f32 v71, v76, v77
	v_mfma_f32_32x32x16_bf16 v[2:17], v[126:129], v[66:69], v[2:17]
	v_exp_f32_e32 v81, v81
	v_add_f32_e32 v228, v228, v78
	v_add_f32_e32 v229, v229, v79
	v_cvt_pk_bf16_f32 v72, v78, v79
	v_add_f32_e32 v228, v228, v80
	v_add_f32_e32 v229, v229, v81
	v_cvt_pk_bf16_f32 v73, v80, v81
	s_waitcnt lgkmcnt(7)
	ds_read_b64_tr_b16 v[114:115], v0 offset:24576
	ds_read_b64_tr_b16 v[116:117], v0 offset:26624
	ds_read_b64_tr_b16 v[118:119], v0 offset:25088
	ds_read_b64_tr_b16 v[120:121], v0 offset:27136
	ds_read_b64_tr_b16 v[122:123], v0 offset:25600
	ds_read_b64_tr_b16 v[124:125], v0 offset:27648
	ds_read_b64_tr_b16 v[126:127], v0 offset:26112
	ds_read_b64_tr_b16 v[128:129], v0 offset:28160
	s_waitcnt lgkmcnt(8)
	v_mfma_f32_32x32x16_bf16 v[50:65], v[146:149], v[70:73], v[50:65]
	v_exp_f32_e32 v82, v82
	v_exp_f32_e32 v83, v83
	v_exp_f32_e32 v84, v84
	v_mfma_f32_32x32x16_bf16 v[34:49], v[150:153], v[70:73], v[34:49]
	v_exp_f32_e32 v85, v85
	v_exp_f32_e32 v86, v86
	v_add_f32_e32 v228, v228, v82
	v_add_f32_e32 v229, v229, v83
	v_cvt_pk_bf16_f32 v74, v82, v83
	v_mfma_f32_32x32x16_bf16 v[18:33], v[154:157], v[70:73], v[18:33]
	v_exp_f32_e32 v87, v87
	v_exp_f32_e32 v88, v88
	v_add_f32_e32 v228, v228, v84
	v_add_f32_e32 v229, v229, v85
	v_cvt_pk_bf16_f32 v75, v84, v85
	v_mfma_f32_32x32x16_bf16 v[2:17], v[158:161], v[70:73], v[2:17]
	v_exp_f32_e32 v89, v89
	v_add_f32_e32 v228, v228, v86
	v_add_f32_e32 v229, v229, v87
	v_cvt_pk_bf16_f32 v76, v86, v87
	v_add_f32_e32 v228, v228, v88
	v_add_f32_e32 v229, v229, v89
	v_cvt_pk_bf16_f32 v77, v88, v89
	s_waitcnt lgkmcnt(7)
	ds_read_b64_tr_b16 v[146:147], v0 offset:28672
	ds_read_b64_tr_b16 v[148:149], v0 offset:30720
	ds_read_b64_tr_b16 v[150:151], v0 offset:29184
	ds_read_b64_tr_b16 v[152:153], v0 offset:31232
	ds_read_b64_tr_b16 v[154:155], v0 offset:29696
	ds_read_b64_tr_b16 v[156:157], v0 offset:31744
	ds_read_b64_tr_b16 v[158:159], v0 offset:30208
	ds_read_b64_tr_b16 v[160:161], v0 offset:32256
	s_waitcnt lgkmcnt(8)
	v_mfma_f32_32x32x16_bf16 v[50:65], v[114:117], v[74:77], v[50:65]
	v_exp_f32_e32 v90, v90
	v_exp_f32_e32 v91, v91
	v_exp_f32_e32 v92, v92
	v_mfma_f32_32x32x16_bf16 v[34:49], v[118:121], v[74:77], v[34:49]
	v_exp_f32_e32 v93, v93
	v_exp_f32_e32 v94, v94
	v_add_f32_e32 v228, v228, v90
	v_add_f32_e32 v229, v229, v91
	v_cvt_pk_bf16_f32 v78, v90, v91
	v_mfma_f32_32x32x16_bf16 v[18:33], v[122:125], v[74:77], v[18:33]
	v_exp_f32_e32 v95, v95
	v_exp_f32_e32 v96, v96
	v_add_f32_e32 v228, v228, v92
	v_add_f32_e32 v229, v229, v93
	v_cvt_pk_bf16_f32 v79, v92, v93
	v_mfma_f32_32x32x16_bf16 v[2:17], v[126:129], v[74:77], v[2:17]
	v_exp_f32_e32 v97, v97
	v_add_f32_e32 v228, v228, v94
	v_add_f32_e32 v229, v229, v95
	v_cvt_pk_bf16_f32 v80, v94, v95
	v_add_f32_e32 v228, v228, v96
	v_add_f32_e32 v229, v229, v97
	v_cvt_pk_bf16_f32 v81, v96, v97
	s_waitcnt lgkmcnt(0)
	v_add_f32_e32 v228, v228, v229
	s_andn2_b64 vcc, exec, s[16:17]
	s_cbranch_vccnz .Lpv3_nodma
; #define LAS __attribute__((address_space(3)))
; #define MFMA32(a, b, c) __builtin_amdgcn_mfma_f32_32x32x16_bf16((a), (b), (c), 0, 0, 0)
; #define ATT_WAIT_BAR(n) asm volatile("s_waitcnt vmcnt(" #n ")\n\ts_barrier" ::: "memory")
; #define ATT_VLOAD(dst, db) do { _Pragma("unroll") for (int ks = 0; ks < 4; ++ks) { \
;                 const s16x4 lo_ = vtr(vb + (2 * ks) * (NDB * 512) + (db) * 512 + vlane), h4_ = vtr(vb + (2 * ks + 1) * (NDB * 512) + (db) * 512 + vlane); \
;                 dst[ks] = (bf16x8){lo_[0], lo_[1], lo_[2], lo_[3], h4_[0], h4_[1], h4_[2], h4_[3]}; } } while (0)
; template <bool DIFF, bool FIXED, bool F32SRC> ...
;     ...
;         const int b2 = (buf >= 1) ? buf - 1 : 2;
;         if (j - 2 >= u.jlo) ATT_DMA(j - 2, b2);
;         }
;         const bool comp = (wact && j <= cq && j >= cq - win);
;         if (comp) {
;             const LAS unsigned char* kb = lds + buf * BUF; const LAS unsigned char* vb = kb + KBUF;
;             const int dqi = qloc - 64 * j - 4 * hi; const float dq = (float)dqi;
;             bf16x8 kf0[2], kf1[2];
; #pragma unroll
;             for (int ks = 0; ks < 2; ++ks) { kf0[ks] = *(const LAS bf16x8*)(kb + koff[ks]); kf1[ks] = *(const LAS bf16x8*)(kb + koff[ks] + 32 * RB); }
;             f32x16 a0, a1;
;             if (DIFF) {
;                 if (j < cq) {
;                     const float base = -slopeL2 * dq - mrun;
; #pragma unroll
;                     for (int r = 0; r < 16; ++r) { const float c = (float)((r & 3) + 8 * (r >> 2)); a0[r] = slopeL2 * c + base; a1[r] = slopeL2 * (c + 32.f) + base; }
;     ...
;             for (int db = 0; db < NDB; ++db) {
;                 ATT_VLOAD(vf, db);
;                 __builtin_amdgcn_sched_barrier(0);
; #pragma unroll
;                 for (int ks = 0; ks < 4; ++ks) o[db] = MFMA32(vf[ks], pf[ks], o[db]);
;                 __builtin_amdgcn_sched_barrier(0);
;             }
;     ...
;         }
;         if (F32SRC) buf ^= 1;
;         else {
;         if (j - 2 >= u.jlo) { if (NCH == 2) ATT_WAIT_BAR(4); else ATT_WAIT_BAR(2); }
;         else ATT_WAIT_BAR(0);
;         buf = (buf == 2) ? 0 : buf + 1;
	v_mfma_f32_32x32x16_bf16 v[50:65], v[146:149], v[78:81], v[50:65]
	v_add_f32_e32 v219, v219, v228
	s_ashr_i32 s13, s12, 31
	s_lshl_b64 s[18:19], s[12:13], 11
	s_add_u32 s66, s50, s18
	s_addc_u32 s67, s60, s19
	s_add_u32 s18, s63, s18
	s_addc_u32 s19, s64, s19
	s_lshl_b32 s13, s28, 15
	s_addk_i32 s13, 0x8000
	s_cmp_gt_i32 s28, 0
	s_cselect_b32 s13, s13, 0x10000
	s_add_i32 s13, s51, s13
	v_lshl_add_u64 v[230:231], v[136:137], 1, s[66:67]
	s_mov_b32 m0, s13
	s_nop 0
	global_load_lds_dwordx4 v[230:231], off
	v_mfma_f32_32x32x16_bf16 v[34:49], v[150:153], v[78:81], v[34:49]
	v_lshl_add_u64 v[230:231], v[138:139], 1, s[18:19]
	s_add_i32 m0, s13, 0x4000
	s_nop 0
	global_load_lds_dwordx4 v[230:231], off
	v_mfma_f32_32x32x16_bf16 v[18:33], v[154:157], v[78:81], v[18:33]
	v_lshl_add_u64 v[230:231], v[140:141], 1, s[66:67]
	s_add_i32 m0, s13, 0x400
	s_nop 0
	global_load_lds_dwordx4 v[230:231], off
	v_mfma_f32_32x32x16_bf16 v[2:17], v[158:161], v[78:81], v[2:17]
	v_lshl_add_u64 v[230:231], v[142:143], 1, s[18:19]
	s_add_i32 m0, s13, 0x4400
	s_nop 0
	global_load_lds_dwordx4 v[230:231], off
	s_add_i32 s16, s28, 1
	s_cmp_lg_u32 s28, 2
	s_cselect_b32 s28, s16, 0
	s_add_i32 s25, s25, -1
	s_sub_i32 s12, s12, 64
	v_add_u32_e32 v226, 64, v226
	s_cmp_ge_i32 s25, s24
	s_cselect_b64 s[16:17], -1, 0
	s_add_i32 s13, s25, 2
	s_cmp_le_i32 s13, s30
	s_cselect_b64 s[18:19], -1, 0
	s_and_b64 s[18:19], s[0:1], s[18:19]
	s_cmp_ge_i32 s13, s29
	s_cselect_b64 s[66:67], -1, 0
	s_and_b64 s[18:19], s[18:19], s[66:67]
	s_andn2_b64 vcc, exec, s[18:19]
	s_cbranch_vccnz .Lnext_nc
	v_cvt_f32_i32_e32 v235, v226
	s_lshl_b32 s18, s28, 15
	s_add_i32 s66, s18, 0
	v_fma_f32 v235, -v135, v235, -v132
	v_add3_u32 v0, s66, v221, v220
	v_add3_u32 v232, s66, v222, v220
	v_add3_u32 v233, s66, v223, v220
	v_add3_u32 v234, s66, v224, v220
	v_add_f32_e32 v80, v174, v235
	v_add_f32_e32 v81, v175, v235
	v_add_f32_e32 v78, v172, v235
	v_add_f32_e32 v79, v173, v235
	v_add_f32_e32 v76, v170, v235
	v_add_f32_e32 v77, v171, v235
	v_add_f32_e32 v74, v168, v235
	v_add_f32_e32 v75, v169, v235
	v_add_f32_e32 v72, v166, v235
	v_add_f32_e32 v73, v167, v235
	v_add_f32_e32 v70, v164, v235
	v_add_f32_e32 v71, v165, v235
	v_add_f32_e32 v68, v162, v235
	v_add_f32_e32 v69, v163, v235
	v_add_f32_e32 v66, v134, v235
	v_add_f32_e32 v67, v135, v235
	s_waitcnt vmcnt(4)
	s_barrier
	ds_read_b128 v[114:117], v0
	ds_read_b128 v[118:121], v232
	ds_read_b128 v[122:125], v233
	ds_read_b128 v[126:129], v234
	ds_read_b128 v[146:149], v0 offset:8192
	ds_read_b128 v[150:153], v232 offset:8192
	ds_read_b128 v[154:157], v233 offset:8192
	ds_read_b128 v[158:161], v234 offset:8192
	s_branch .Lqk_pre
.Lnext_nc:
	s_waitcnt vmcnt(4)
	s_barrier
	s_branch .Lbb415
